# work-queue fetch: thread 0's returning atomic issued before the first barrier of the fetch so its round trip overlaps the wait for the other waves
# baseline (speedup 1.0000x reference)
.LBB0_159:
	s_mov_b64 s[0:1], exec
	v_readlane_b32 s2, v250, 11
	v_readlane_b32 s3, v250, 12
	s_and_b64 s[2:3], s[0:1], s[2:3]
	s_mov_b64 exec, s[2:3]
	s_cbranch_execz .Lwqpre0_done
	s_mov_b64 s[24:25], exec
	v_mbcnt_lo_u32_b32 v0, s24, 0
	v_mbcnt_hi_u32_b32 v0, s25, v0
	v_cmp_eq_u32_e32 vcc, 0, v0
	s_and_saveexec_b64 s[2:3], vcc
	s_cbranch_execz .Lwqpre0_done
	s_bcnt1_i32_b64 s24, s[24:25]
	v_mov_b32_e32 v1, s24
	global_atomic_add v1, v129, v1, s[82:83] sc0
.Lwqpre0_done:
	s_mov_b64 exec, s[0:1]
	s_waitcnt lgkmcnt(0)
	s_barrier
	s_mov_b64 s[0:1], exec
	v_readlane_b32 s2, v250, 11
	v_readlane_b32 s3, v250, 12
	s_and_b64 s[2:3], s[0:1], s[2:3]
	s_mov_b64 exec, s[2:3]
	s_cbranch_execz .LBB0_163
	s_mov_b64 s[24:25], exec
	v_mbcnt_lo_u32_b32 v0, s24, 0
	v_mbcnt_hi_u32_b32 v0, s25, v0
	v_cmp_eq_u32_e32 vcc, 0, v0
	s_and_saveexec_b64 s[2:3], vcc
	s_cbranch_execz .LBB0_162
	s_bcnt1_i32_b64 s24, s[24:25]

.LBB0_431:
	s_mov_b64 s[0:1], exec
	v_readlane_b32 s2, v250, 11
	v_readlane_b32 s3, v250, 12
	s_and_b64 s[2:3], s[0:1], s[2:3]
	s_mov_b64 exec, s[2:3]
	s_cbranch_execz .Lwqpre1_done
	s_mov_b64 s[24:25], exec
	v_mbcnt_lo_u32_b32 v0, s24, 0
	v_mbcnt_hi_u32_b32 v0, s25, v0
	v_cmp_eq_u32_e32 vcc, 0, v0
	s_and_saveexec_b64 s[2:3], vcc
	s_cbranch_execz .Lwqpre1_done
	s_bcnt1_i32_b64 s24, s[24:25]
	v_readlane_b32 s16, v254, 57
	v_mov_b32_e32 v1, s24
	v_readlane_b32 s17, v254, 58
	s_nop 4
	global_atomic_add v1, v129, v1, s[16:17] sc0
.Lwqpre1_done:
	s_mov_b64 exec, s[0:1]
	s_waitcnt lgkmcnt(0)
	s_barrier
	s_mov_b64 s[0:1], exec
	v_readlane_b32 s2, v250, 11
	v_readlane_b32 s3, v250, 12
	s_and_b64 s[2:3], s[0:1], s[2:3]
	s_mov_b64 exec, s[2:3]
	s_cbranch_execz .LBB0_435
	s_mov_b64 s[24:25], exec
	v_mbcnt_lo_u32_b32 v0, s24, 0
	v_mbcnt_hi_u32_b32 v0, s25, v0
	v_cmp_eq_u32_e32 vcc, 0, v0
	s_and_saveexec_b64 s[2:3], vcc
	s_cbranch_execz .LBB0_434
	s_bcnt1_i32_b64 s24, s[24:25]
	v_readlane_b32 s16, v254, 57
	v_readlane_b32 s17, v254, 58
	s_nop 4
